# flat2global atomics: the 8 rowss flat_atomic_add_f32 of the P3 epilogue issued as global atomics
# speedup vs baseline: 1.0037x; 1.0037x over previous
; __device__ __forceinline__ unsigned cvtpk(float lo, float hi) { f32x2 v = {lo, hi}; bf16x2_t b = __builtin_convertvector(v, bf16x2_t); return __builtin_bit_cast(unsigned, b); }
;     __device__ __forceinline__ void operator()(const Acc& acc, const Unit& u, int wr, int wc, int fr, int fq) const {
;     ...
;         const int colbase = u.pn * 256 + wc * 64 + 8 * fq;
; #pragma unroll
;         for (int ai = 0; ai < 2; ++ai) {
;             f32x4 xv[4][2][2];
; #pragma unroll
;             for (int m = 0; m < 4; ++m) { const size_t off = (size_t)(u.pm * 256 + ai * 128 + wr * 64 + m * 16 + fr) * DM + colbase;
; #pragma unroll
;                 for (int bj = 0; bj < 2; ++bj) { xv[m][bj][0] = __builtin_nontemporal_load((const f32x4*)(x + off + 32 * bj)); xv[m][bj][1] = __builtin_nontemporal_load((const f32x4*)(x + off + 32 * bj + 4)); } }
; #pragma unroll
;             for (int m = 0; m < 4; ++m) {
;                 const int row = u.pm * 256 + ai * 128 + wr * 64 + m * 16 + fr;
;                 float ss = 0.f;
; #pragma unroll
;                 for (int bj = 0; bj < 2; ++bj) {
;                     const size_t off = (size_t)row * DM + colbase + 32 * bj;
;                     const f32x4 h0 = xv[m][bj][0] + acc[ai][bj][m][0], h1 = xv[m][bj][1] + acc[ai][bj][m][1];
;                     u32x4 w; w.x = cvtpk(h0.x, h0.y); w.y = cvtpk(h0.z, h0.w); w.z = cvtpk(h1.x, h1.y); w.w = cvtpk(h1.z, h1.w);
;                     *(u32x4*)(HB + off) = w;
;                     ss += (h0.x * h0.x + h0.y * h0.y) + (h0.z * h0.z + h0.w * h0.w) + (h1.x * h1.x + h1.y * h1.y) + (h1.z * h1.z + h1.w * h1.w);
;                 }
;                 ss = quad_sum(ss);
;                 if (fq == 0) atomicAdd(rowss + row, ss);
.LBB0_725:
	v_mov_b32_e32 v128, v200
	s_lshl_b32 s13, s22, 8
	s_or_b32 s13, s13, s86
	v_and_b32_e32 v129, 15, v128
	v_bfe_u32 v202, v128, 4, 2
	s_nop 0
	v_lshl_add_u32 v188, v202, 3, s13
	s_lshl_b32 s13, s20, 8
	s_add_i32 s13, s13, s79
	v_add_u32_e32 v192, s13, v129
	v_ashrrev_i32_e32 v189, 31, v188
	v_ashrrev_i32_e32 v193, 31, v192
	v_lshl_add_u64 v[190:191], v[188:189], 2, s[8:9]
	v_lshlrev_b64 v[128:129], 13, v[192:193]
	v_lshl_add_u64 v[128:129], v[190:191], 0, v[128:129]
	global_load_dwordx4 v[206:209], v[128:129], off nt
	global_load_dwordx4 v[210:213], v[128:129], off offset:16 nt
	global_load_dwordx4 v[214:217], v[128:129], off offset:128 nt
	global_load_dwordx4 v[218:221], v[128:129], off offset:144 nt
	v_add_u32_e32 v198, 16, v192
	v_add_u32_e32 v196, 32, v192
	v_add_u32_e32 v194, 48, v192
	v_ashrrev_i32_e32 v199, 31, v198
	v_ashrrev_i32_e32 v197, 31, v196
	v_ashrrev_i32_e32 v195, 31, v194
	v_lshlrev_b64 v[128:129], 13, v[198:199]
	v_lshlrev_b64 v[130:131], 13, v[196:197]
	v_lshlrev_b64 v[132:133], 13, v[194:195]
	v_lshl_add_u64 v[128:129], v[190:191], 0, v[128:129]
	v_lshl_add_u64 v[130:131], v[190:191], 0, v[130:131]
	v_lshl_add_u64 v[222:223], v[190:191], 0, v[132:133]
	global_load_dwordx4 v[172:175], v[128:129], off nt
	global_load_dwordx4 v[168:171], v[128:129], off offset:16 nt
	global_load_dwordx4 v[164:167], v[128:129], off offset:128 nt
	global_load_dwordx4 v[160:163], v[128:129], off offset:144 nt
	global_load_dwordx4 v[156:159], v[130:131], off nt
	global_load_dwordx4 v[152:155], v[130:131], off offset:16 nt
	global_load_dwordx4 v[148:151], v[130:131], off offset:128 nt
	global_load_dwordx4 v[144:147], v[130:131], off offset:144 nt
	global_load_dwordx4 v[140:143], v[222:223], off nt
	global_load_dwordx4 v[136:139], v[222:223], off offset:16 nt
	global_load_dwordx4 v[132:135], v[222:223], off offset:128 nt
	s_nop 0
	global_load_dwordx4 v[128:131], v[222:223], off offset:144 nt
	v_cmp_eq_u32_e32 vcc, 0, v202
	v_lshlrev_b64 v[222:223], 12, v[192:193]
	v_lshl_add_u64 v[222:223], s[10:11], 0, v[222:223]
	v_lshl_add_u64 v[222:223], v[188:189], 1, v[222:223]
	s_waitcnt vmcnt(0) lgkmcnt(0)
	v_pk_add_f32 v[126:127], v[126:127], v[208:209]
	v_pk_add_f32 v[124:125], v[124:125], v[206:207]
	v_pk_add_f32 v[118:119], v[118:119], v[216:217]
	v_pk_add_f32 v[206:207], v[116:117], v[214:215]
	v_pk_add_f32 v[120:121], v[120:121], v[210:211]
	v_pk_add_f32 v[210:211], v[112:113], v[218:219]
	v_cvt_pk_bf16_f32 v112, v124, v125
	v_cvt_pk_bf16_f32 v113, v126, v127
	v_mul_f32_e32 v125, v125, v125
	v_mul_f32_e32 v127, v127, v127
	v_cvt_pk_bf16_f32 v117, v118, v119
	v_mul_f32_e32 v202, v207, v207
	v_mul_f32_e32 v119, v119, v119
	v_pk_add_f32 v[122:123], v[122:123], v[212:213]
	v_pk_add_f32 v[208:209], v[114:115], v[220:221]
	v_cvt_pk_bf16_f32 v114, v120, v121
	v_mul_f32_e32 v121, v121, v121
	v_cvt_pk_bf16_f32 v116, v206, v207
	v_mul_f32_e32 v207, v211, v211
	v_fmac_f32_e32 v125, v124, v124
	v_fmac_f32_e32 v127, v126, v126
	v_fmac_f32_e32 v202, v206, v206
	v_fmac_f32_e32 v119, v118, v118
	v_cvt_pk_bf16_f32 v115, v122, v123
	v_mul_f32_e32 v123, v123, v123
	v_mul_f32_e32 v212, v209, v209
	v_fmac_f32_e32 v121, v120, v120
	v_fmac_f32_e32 v207, v210, v210
	v_add_f32_e32 v118, v125, v127
	v_add_f32_e32 v119, v202, v119
	v_fmac_f32_e32 v123, v122, v122
	v_fmac_f32_e32 v212, v208, v208
	v_add_f32_e32 v118, v118, v121
	v_add_f32_e32 v119, v119, v207
	v_add_f32_e32 v118, v123, v118
	v_add_f32_e32 v119, v212, v119
	v_add_f32_e32 v120, v118, v119
	ds_swizzle_b32 v121, v120 offset:swizzle(SWAP,16)
	v_cvt_pk_bf16_f32 v118, v210, v211
	v_cvt_pk_bf16_f32 v119, v208, v209
	v_mov_b64_e32 v[224:225], v[112:113]
	v_mov_b64_e32 v[226:227], v[114:115]
	flat_store_dwordx4 v[222:223], v[112:115]
	v_mov_b64_e32 v[214:215], v[116:117]
	v_mov_b64_e32 v[216:217], v[118:119]
	flat_store_dwordx4 v[222:223], v[116:119] offset:64
	s_waitcnt lgkmcnt(0)
	v_add_f32_e32 v114, v120, v121
	v_mov_b32_e32 v115, v114
	s_nop 1
	v_permlane32_swap_b32_e32 v114, v115
	v_lshl_add_u64 v[112:113], v[192:193], 2, s[6:7]
	s_and_saveexec_b64 s[20:21], vcc
	s_cbranch_execz .LBB0_727
	v_add_f32_e32 v114, v114, v115
	global_atomic_add_f32 v[112:113], v114, off
.LBB0_727:
	s_or_b64 exec, exec, s[20:21]
	v_lshlrev_b64 v[114:115], 12, v[198:199]
	v_pk_add_f32 v[110:111], v[110:111], v[174:175]
	v_pk_add_f32 v[108:109], v[108:109], v[172:173]
	v_pk_add_f32 v[116:117], v[106:107], v[170:171]
	v_pk_add_f32 v[118:119], v[104:105], v[168:169]
	v_lshl_add_u64 v[114:115], s[10:11], 0, v[114:115]
	v_cvt_pk_bf16_f32 v104, v108, v109
	v_cvt_pk_bf16_f32 v105, v110, v111
	v_cvt_pk_bf16_f32 v106, v118, v119
	v_cvt_pk_bf16_f32 v107, v116, v117
	v_lshl_add_u64 v[114:115], v[188:189], 1, v[114:115]
	v_mov_b64_e32 v[228:229], v[104:105]
	v_mov_b64_e32 v[230:231], v[106:107]
	flat_store_dwordx4 v[114:115], v[104:107]
	v_pk_add_f32 v[100:101], v[100:101], v[164:165]
	v_pk_add_f32 v[102:103], v[102:103], v[166:167]
	v_mul_f32_e32 v104, v109, v109
	v_mul_f32_e32 v105, v111, v111
	v_fmac_f32_e32 v104, v108, v108
	v_fmac_f32_e32 v105, v110, v110
	v_add_f32_e32 v104, v104, v105
	v_mul_f32_e32 v105, v119, v119
	v_fmac_f32_e32 v105, v118, v118
	v_add_f32_e32 v104, v104, v105
	v_mul_f32_e32 v105, v117, v117
	v_fmac_f32_e32 v105, v116, v116
	v_add_f32_e32 v106, v105, v104
	v_pk_add_f32 v[104:105], v[98:99], v[162:163]
	v_pk_add_f32 v[98:99], v[96:97], v[160:161]
	v_mul_f32_e32 v97, v101, v101
	v_cvt_pk_bf16_f32 v96, v100, v101
	v_fmac_f32_e32 v97, v100, v100
	v_mul_f32_e32 v100, v103, v103
	v_fmac_f32_e32 v100, v102, v102
	v_add_f32_e32 v97, v97, v100
	v_mul_f32_e32 v100, v99, v99
	v_fmac_f32_e32 v100, v98, v98
	v_add_f32_e32 v97, v97, v100
	v_mul_f32_e32 v100, v105, v105
	v_fmac_f32_e32 v100, v104, v104
	v_add_f32_e32 v97, v100, v97
	v_add_f32_e32 v100, v106, v97
	ds_swizzle_b32 v101, v100 offset:swizzle(SWAP,16)
	v_cvt_pk_bf16_f32 v97, v102, v103
	v_cvt_pk_bf16_f32 v98, v98, v99
	v_cvt_pk_bf16_f32 v99, v104, v105
	v_mov_b64_e32 v[232:233], v[96:97]
	v_mov_b64_e32 v[234:235], v[98:99]
	flat_store_dwordx4 v[114:115], v[96:99] offset:64
	s_waitcnt lgkmcnt(0)
	s_nop 0
	v_add_f32_e32 v96, v100, v101
	v_mov_b32_e32 v97, v96
	s_nop 1
	v_permlane32_swap_b32_e32 v96, v97
	s_and_saveexec_b64 s[20:21], vcc
	s_cbranch_execz .LBB0_729
	v_add_f32_e32 v96, v96, v97
	global_atomic_add_f32 v[112:113], v96, off offset:64
; __device__ __forceinline__ unsigned cvtpk(float lo, float hi) { f32x2 v = {lo, hi}; bf16x2_t b = __builtin_convertvector(v, bf16x2_t); return __builtin_bit_cast(unsigned, b); }
;     __device__ __forceinline__ void operator()(const Acc& acc, const Unit& u, int wr, int wc, int fr, int fq) const {
;     ...
;             for (int m = 0; m < 4; ++m) {
;                 const int row = u.pm * 256 + ai * 128 + wr * 64 + m * 16 + fr;
;                 float ss = 0.f;
; #pragma unroll
;                 for (int bj = 0; bj < 2; ++bj) {
;                     const size_t off = (size_t)row * DM + colbase + 32 * bj;
;                     const f32x4 h0 = xv[m][bj][0] + acc[ai][bj][m][0], h1 = xv[m][bj][1] + acc[ai][bj][m][1];
;                     u32x4 w; w.x = cvtpk(h0.x, h0.y); w.y = cvtpk(h0.z, h0.w); w.z = cvtpk(h1.x, h1.y); w.w = cvtpk(h1.z, h1.w);
;                     *(u32x4*)(HB + off) = w;
;                     ss += (h0.x * h0.x + h0.y * h0.y) + (h0.z * h0.z + h0.w * h0.w) + (h1.x * h1.x + h1.y * h1.y) + (h1.z * h1.z + h1.w * h1.w);
;                 }
;                 ss = quad_sum(ss);
;                 if (fq == 0) atomicAdd(rowss + row, ss);
.LBB0_729:
	s_or_b64 exec, exec, s[20:21]
	v_lshlrev_b64 v[96:97], 12, v[196:197]
	v_pk_add_f32 v[94:95], v[94:95], v[158:159]
	v_pk_add_f32 v[92:93], v[92:93], v[156:157]
	v_pk_add_f32 v[98:99], v[90:91], v[154:155]
	v_pk_add_f32 v[100:101], v[88:89], v[152:153]
	v_lshl_add_u64 v[96:97], s[10:11], 0, v[96:97]
	v_cvt_pk_bf16_f32 v88, v92, v93
	v_cvt_pk_bf16_f32 v89, v94, v95
	v_cvt_pk_bf16_f32 v90, v100, v101
	v_cvt_pk_bf16_f32 v91, v98, v99
	v_lshl_add_u64 v[96:97], v[188:189], 1, v[96:97]
	v_mov_b64_e32 v[236:237], v[88:89]
	v_mov_b64_e32 v[238:239], v[90:91]
	flat_store_dwordx4 v[96:97], v[88:91]
	v_pk_add_f32 v[84:85], v[84:85], v[148:149]
	v_pk_add_f32 v[86:87], v[86:87], v[150:151]
	v_mul_f32_e32 v88, v93, v93
	v_mul_f32_e32 v89, v95, v95
	v_fmac_f32_e32 v88, v92, v92
	v_fmac_f32_e32 v89, v94, v94
	v_add_f32_e32 v88, v88, v89
	v_mul_f32_e32 v89, v101, v101
	v_fmac_f32_e32 v89, v100, v100
	v_add_f32_e32 v88, v88, v89
	v_mul_f32_e32 v89, v99, v99
	v_fmac_f32_e32 v89, v98, v98
	v_add_f32_e32 v90, v89, v88
	v_pk_add_f32 v[88:89], v[82:83], v[146:147]
	v_pk_add_f32 v[82:83], v[80:81], v[144:145]
	v_mul_f32_e32 v81, v85, v85
	v_cvt_pk_bf16_f32 v80, v84, v85
	v_fmac_f32_e32 v81, v84, v84
	v_mul_f32_e32 v84, v87, v87
	v_fmac_f32_e32 v84, v86, v86
	v_add_f32_e32 v81, v81, v84
	v_mul_f32_e32 v84, v83, v83
	v_fmac_f32_e32 v84, v82, v82
	v_add_f32_e32 v81, v81, v84
	v_mul_f32_e32 v84, v89, v89
	v_fmac_f32_e32 v84, v88, v88
	v_add_f32_e32 v81, v84, v81
	v_add_f32_e32 v84, v90, v81
	ds_swizzle_b32 v85, v84 offset:swizzle(SWAP,16)
	v_cvt_pk_bf16_f32 v81, v86, v87
	v_cvt_pk_bf16_f32 v82, v82, v83
	v_cvt_pk_bf16_f32 v83, v88, v89
	v_mov_b64_e32 v[240:241], v[80:81]
	v_mov_b64_e32 v[242:243], v[82:83]
	flat_store_dwordx4 v[96:97], v[80:83] offset:64
	s_waitcnt lgkmcnt(0)
	s_nop 0
	v_add_f32_e32 v80, v84, v85
	v_mov_b32_e32 v81, v80
	s_nop 1
	v_permlane32_swap_b32_e32 v80, v81
	s_and_saveexec_b64 s[20:21], vcc
	s_cbranch_execz .LBB0_731
	v_add_f32_e32 v80, v80, v81
	global_atomic_add_f32 v[112:113], v80, off offset:128
.LBB0_731:
	s_or_b64 exec, exec, s[20:21]
	v_lshlrev_b64 v[80:81], 12, v[194:195]
	v_pk_add_f32 v[78:79], v[78:79], v[142:143]
	v_pk_add_f32 v[76:77], v[76:77], v[140:141]
	v_pk_add_f32 v[82:83], v[74:75], v[138:139]
	v_pk_add_f32 v[84:85], v[72:73], v[136:137]
	v_lshl_add_u64 v[80:81], s[10:11], 0, v[80:81]
	v_cvt_pk_bf16_f32 v72, v76, v77
	v_cvt_pk_bf16_f32 v73, v78, v79
	v_cvt_pk_bf16_f32 v74, v84, v85
	v_cvt_pk_bf16_f32 v75, v82, v83
	v_lshl_add_u64 v[80:81], v[188:189], 1, v[80:81]
	v_mov_b64_e32 v[210:211], v[72:73]
	v_mov_b64_e32 v[212:213], v[74:75]
	flat_store_dwordx4 v[80:81], v[72:75]
	v_pk_add_f32 v[68:69], v[68:69], v[132:133]
	v_pk_add_f32 v[70:71], v[70:71], v[134:135]
	v_mul_f32_e32 v72, v77, v77
	v_mul_f32_e32 v73, v79, v79
	v_fmac_f32_e32 v72, v76, v76
	v_fmac_f32_e32 v73, v78, v78
	v_add_f32_e32 v72, v72, v73
	v_mul_f32_e32 v73, v85, v85
	v_fmac_f32_e32 v73, v84, v84
	v_add_f32_e32 v72, v72, v73
	v_mul_f32_e32 v73, v83, v83
	v_fmac_f32_e32 v73, v82, v82
	v_add_f32_e32 v74, v73, v72
	v_pk_add_f32 v[72:73], v[66:67], v[130:131]
	v_pk_add_f32 v[66:67], v[64:65], v[128:129]
	v_mul_f32_e32 v65, v69, v69
	v_cvt_pk_bf16_f32 v64, v68, v69
	v_fmac_f32_e32 v65, v68, v68
	v_mul_f32_e32 v68, v71, v71
	v_fmac_f32_e32 v68, v70, v70
	v_add_f32_e32 v65, v65, v68
	v_mul_f32_e32 v68, v67, v67
	v_fmac_f32_e32 v68, v66, v66
	v_add_f32_e32 v65, v65, v68
	v_mul_f32_e32 v68, v73, v73
	v_fmac_f32_e32 v68, v72, v72
	v_add_f32_e32 v65, v68, v65
	v_add_f32_e32 v68, v74, v65
	ds_swizzle_b32 v69, v68 offset:swizzle(SWAP,16)
	v_cvt_pk_bf16_f32 v65, v70, v71
	v_cvt_pk_bf16_f32 v66, v66, v67
	v_cvt_pk_bf16_f32 v67, v72, v73
	v_mov_b64_e32 v[244:245], v[64:65]
	v_mov_b64_e32 v[246:247], v[66:67]
	flat_store_dwordx4 v[80:81], v[64:67] offset:64
	s_waitcnt lgkmcnt(0)
	s_nop 0
	v_add_f32_e32 v64, v68, v69
	v_mov_b32_e32 v65, v64
	s_nop 1
	v_permlane32_swap_b32_e32 v64, v65
	s_and_saveexec_b64 s[20:21], vcc
	s_cbranch_execz .LBB0_733
	v_add_f32_e32 v64, v64, v65
	global_atomic_add_f32 v[112:113], v64, off offset:192
; __device__ __forceinline__ unsigned cvtpk(float lo, float hi) { f32x2 v = {lo, hi}; bf16x2_t b = __builtin_convertvector(v, bf16x2_t); return __builtin_bit_cast(unsigned, b); }
;     __device__ __forceinline__ void operator()(const Acc& acc, const Unit& u, int wr, int wc, int fr, int fq) const {
;     ...
;         for (int ai = 0; ai < 2; ++ai) {
;             f32x4 xv[4][2][2];
; #pragma unroll
;             for (int m = 0; m < 4; ++m) { const size_t off = (size_t)(u.pm * 256 + ai * 128 + wr * 64 + m * 16 + fr) * DM + colbase;
; #pragma unroll
;                 for (int bj = 0; bj < 2; ++bj) { xv[m][bj][0] = __builtin_nontemporal_load((const f32x4*)(x + off + 32 * bj)); xv[m][bj][1] = __builtin_nontemporal_load((const f32x4*)(x + off + 32 * bj + 4)); } }
; #pragma unroll
;             for (int m = 0; m < 4; ++m) {
;                 const int row = u.pm * 256 + ai * 128 + wr * 64 + m * 16 + fr;
;                 float ss = 0.f;
; #pragma unroll
;                 for (int bj = 0; bj < 2; ++bj) {
;                     const size_t off = (size_t)row * DM + colbase + 32 * bj;
;                     const f32x4 h0 = xv[m][bj][0] + acc[ai][bj][m][0], h1 = xv[m][bj][1] + acc[ai][bj][m][1];
;                     u32x4 w; w.x = cvtpk(h0.x, h0.y); w.y = cvtpk(h0.z, h0.w); w.z = cvtpk(h1.x, h1.y); w.w = cvtpk(h1.z, h1.w);
;                     *(u32x4*)(HB + off) = w;
;                     ss += (h0.x * h0.x + h0.y * h0.y) + (h0.z * h0.z + h0.w * h0.w) + (h1.x * h1.x + h1.y * h1.y) + (h1.z * h1.z + h1.w * h1.w);
;                 }
;                 ss = quad_sum(ss);
;                 if (fq == 0) atomicAdd(rowss + row, ss);
.LBB0_733:
	s_or_b64 exec, exec, s[20:21]
	v_add_u32_e32 v136, 0x80, v192
	v_ashrrev_i32_e32 v137, 31, v136
	v_lshlrev_b64 v[64:65], 13, v[136:137]
	v_lshl_add_u64 v[64:65], v[190:191], 0, v[64:65]
	global_load_dwordx4 v[120:123], v[64:65], off nt
	global_load_dwordx4 v[124:127], v[64:65], off offset:16 nt
	global_load_dwordx4 v[128:131], v[64:65], off offset:128 nt
	global_load_dwordx4 v[132:135], v[64:65], off offset:144 nt
	v_add_u32_e32 v118, 0x90, v192
	v_add_u32_e32 v116, 0xa0, v192
	v_add_u32_e32 v114, 0xb0, v192
	v_ashrrev_i32_e32 v119, 31, v118
	v_ashrrev_i32_e32 v117, 31, v116
	v_ashrrev_i32_e32 v115, 31, v114
	v_lshlrev_b64 v[64:65], 13, v[118:119]
	v_lshlrev_b64 v[66:67], 13, v[116:117]
	v_lshlrev_b64 v[68:69], 13, v[114:115]
	v_lshl_add_u64 v[64:65], v[190:191], 0, v[64:65]
	v_lshl_add_u64 v[66:67], v[190:191], 0, v[66:67]
	v_lshl_add_u64 v[138:139], v[190:191], 0, v[68:69]
	global_load_dwordx4 v[108:111], v[64:65], off nt
	global_load_dwordx4 v[104:107], v[64:65], off offset:16 nt
	global_load_dwordx4 v[100:103], v[64:65], off offset:128 nt
	global_load_dwordx4 v[96:99], v[64:65], off offset:144 nt
	global_load_dwordx4 v[92:95], v[66:67], off nt
	global_load_dwordx4 v[88:91], v[66:67], off offset:16 nt
	global_load_dwordx4 v[84:87], v[66:67], off offset:128 nt
	global_load_dwordx4 v[80:83], v[66:67], off offset:144 nt
	global_load_dwordx4 v[76:79], v[138:139], off nt
	global_load_dwordx4 v[72:75], v[138:139], off offset:16 nt
	global_load_dwordx4 v[68:71], v[138:139], off offset:128 nt
	s_nop 0
	global_load_dwordx4 v[64:67], v[138:139], off offset:144 nt
	v_lshlrev_b64 v[136:137], 12, v[136:137]
	v_lshl_add_u64 v[136:137], s[10:11], 0, v[136:137]
	v_lshl_add_u64 v[136:137], v[188:189], 1, v[136:137]
	s_waitcnt vmcnt(0) lgkmcnt(0)
	v_pk_add_f32 v[62:63], v[62:63], v[122:123]
	v_pk_add_f32 v[60:61], v[60:61], v[120:121]
	v_pk_add_f32 v[54:55], v[54:55], v[130:131]
	v_pk_add_f32 v[120:121], v[52:53], v[128:129]
	v_pk_add_f32 v[56:57], v[56:57], v[124:125]
	v_pk_add_f32 v[124:125], v[48:49], v[132:133]
	v_cvt_pk_bf16_f32 v48, v60, v61
	v_cvt_pk_bf16_f32 v49, v62, v63
	v_mul_f32_e32 v61, v61, v61
	v_mul_f32_e32 v63, v63, v63
	v_cvt_pk_bf16_f32 v52, v120, v121
	v_cvt_pk_bf16_f32 v53, v54, v55
	v_mul_f32_e32 v121, v121, v121
	v_mul_f32_e32 v55, v55, v55
	v_pk_add_f32 v[58:59], v[58:59], v[126:127]
	v_pk_add_f32 v[122:123], v[50:51], v[134:135]
	v_cvt_pk_bf16_f32 v50, v56, v57
	v_mul_f32_e32 v57, v57, v57
	v_mul_f32_e32 v126, v125, v125
	v_fmac_f32_e32 v61, v60, v60
	v_fmac_f32_e32 v63, v62, v62
	v_fmac_f32_e32 v121, v120, v120
	v_fmac_f32_e32 v55, v54, v54
	v_cvt_pk_bf16_f32 v51, v58, v59
	v_mul_f32_e32 v59, v59, v59
	v_mul_f32_e32 v127, v123, v123
	v_fmac_f32_e32 v57, v56, v56
	v_fmac_f32_e32 v126, v124, v124
	v_add_f32_e32 v54, v61, v63
	v_add_f32_e32 v55, v121, v55
	v_fmac_f32_e32 v59, v58, v58
	v_fmac_f32_e32 v127, v122, v122
	v_add_f32_e32 v54, v54, v57
	v_add_f32_e32 v55, v55, v126
	v_add_f32_e32 v54, v59, v54
	v_add_f32_e32 v55, v127, v55
	v_add_f32_e32 v56, v54, v55
	ds_swizzle_b32 v57, v56 offset:swizzle(SWAP,16)
	v_cvt_pk_bf16_f32 v54, v124, v125
	v_cvt_pk_bf16_f32 v55, v122, v123
	v_mov_b64_e32 v[248:249], v[48:49]
	v_mov_b64_e32 v[252:253], v[50:51]
	flat_store_dwordx4 v[136:137], v[48:51]
	v_mov_b64_e32 v[218:219], v[52:53]
	v_mov_b64_e32 v[220:221], v[54:55]
	flat_store_dwordx4 v[136:137], v[52:55] offset:64
	s_waitcnt lgkmcnt(0)
	v_add_f32_e32 v48, v56, v57
	v_mov_b32_e32 v49, v48
	s_nop 1
	v_permlane32_swap_b32_e32 v48, v49
	s_and_saveexec_b64 s[20:21], vcc
	s_cbranch_execz .LBB0_735
	v_add_f32_e32 v48, v48, v49
	global_atomic_add_f32 v[112:113], v48, off offset:512
.LBB0_735:
	s_or_b64 exec, exec, s[20:21]
	v_lshlrev_b64 v[48:49], 12, v[118:119]
	v_pk_add_f32 v[46:47], v[46:47], v[110:111]
	v_pk_add_f32 v[44:45], v[44:45], v[108:109]
	v_pk_add_f32 v[50:51], v[42:43], v[106:107]
	v_pk_add_f32 v[52:53], v[40:41], v[104:105]
	v_lshl_add_u64 v[48:49], s[10:11], 0, v[48:49]
	v_cvt_pk_bf16_f32 v40, v44, v45
	v_cvt_pk_bf16_f32 v41, v46, v47
	v_cvt_pk_bf16_f32 v42, v52, v53
	v_cvt_pk_bf16_f32 v43, v50, v51
	v_lshl_add_u64 v[48:49], v[188:189], 1, v[48:49]
	v_mov_b64_e32 v[222:223], v[40:41]
	v_mov_b64_e32 v[250:251], v[42:43]
	flat_store_dwordx4 v[48:49], v[40:43]
	v_pk_add_f32 v[36:37], v[36:37], v[100:101]
	v_pk_add_f32 v[38:39], v[38:39], v[102:103]
	v_mul_f32_e32 v40, v45, v45
	v_mul_f32_e32 v41, v47, v47
	v_fmac_f32_e32 v40, v44, v44
	v_fmac_f32_e32 v41, v46, v46
	v_add_f32_e32 v40, v40, v41
	v_mul_f32_e32 v41, v53, v53
	v_fmac_f32_e32 v41, v52, v52
	v_add_f32_e32 v40, v40, v41
	v_mul_f32_e32 v41, v51, v51
	v_fmac_f32_e32 v41, v50, v50
	v_add_f32_e32 v42, v41, v40
	v_pk_add_f32 v[40:41], v[34:35], v[98:99]
	v_pk_add_f32 v[34:35], v[32:33], v[96:97]
	v_mul_f32_e32 v33, v37, v37
	v_cvt_pk_bf16_f32 v32, v36, v37
	v_fmac_f32_e32 v33, v36, v36
	v_mul_f32_e32 v36, v39, v39
	v_fmac_f32_e32 v36, v38, v38
	v_add_f32_e32 v33, v33, v36
	v_mul_f32_e32 v36, v35, v35
	v_fmac_f32_e32 v36, v34, v34
	v_add_f32_e32 v33, v33, v36
	v_mul_f32_e32 v36, v41, v41
	v_fmac_f32_e32 v36, v40, v40
	v_add_f32_e32 v33, v36, v33
	v_add_f32_e32 v36, v42, v33
	ds_swizzle_b32 v37, v36 offset:swizzle(SWAP,16)
	v_cvt_pk_bf16_f32 v33, v38, v39
	v_cvt_pk_bf16_f32 v34, v34, v35
	v_cvt_pk_bf16_f32 v35, v40, v41
	v_mov_b32_e32 v206, 0x20000
	v_lshl_add_u32 v206, v200, 4, v206
	v_lshl_add_u32 v206, s79, 6, v206
	v_lshl_add_u32 v206, s86, 4, v206
	ds_write_b128 v206, v[32:35]
	flat_store_dwordx4 v[48:49], v[32:35] offset:64
	s_waitcnt lgkmcnt(0)
	s_nop 0
	v_add_f32_e32 v32, v36, v37
	v_mov_b32_e32 v33, v32
	s_nop 1
	v_permlane32_swap_b32_e32 v32, v33
	s_and_saveexec_b64 s[20:21], vcc
	s_cbranch_execz .LBB0_737
	v_add_f32_e32 v32, v32, v33
	global_atomic_add_f32 v[112:113], v32, off offset:576

; __device__ __forceinline__ unsigned cvtpk(float lo, float hi) { f32x2 v = {lo, hi}; bf16x2_t b = __builtin_convertvector(v, bf16x2_t); return __builtin_bit_cast(unsigned, b); }
;     __device__ __forceinline__ void operator()(const Acc& acc, const Unit& u, int wr, int wc, int fr, int fq) const {
;     ...
;             for (int m = 0; m < 4; ++m) {
;                 const int row = u.pm * 256 + ai * 128 + wr * 64 + m * 16 + fr;
;                 float ss = 0.f;
; #pragma unroll
;                 for (int bj = 0; bj < 2; ++bj) {
;                     const size_t off = (size_t)row * DM + colbase + 32 * bj;
;                     const f32x4 h0 = xv[m][bj][0] + acc[ai][bj][m][0], h1 = xv[m][bj][1] + acc[ai][bj][m][1];
;                     u32x4 w; w.x = cvtpk(h0.x, h0.y); w.y = cvtpk(h0.z, h0.w); w.z = cvtpk(h1.x, h1.y); w.w = cvtpk(h1.z, h1.w);
;                     *(u32x4*)(HB + off) = w;
;                     ss += (h0.x * h0.x + h0.y * h0.y) + (h0.z * h0.z + h0.w * h0.w) + (h1.x * h1.x + h1.y * h1.y) + (h1.z * h1.z + h1.w * h1.w);
;                 }
;                 ss = quad_sum(ss);
;                 if (fq == 0) atomicAdd(rowss + row, ss);
.Lhbk_ws:
	flat_store_dwordx4 v[32:33], v[24:27]
	v_pk_add_f32 v[20:21], v[20:21], v[84:85]
	v_pk_add_f32 v[22:23], v[22:23], v[86:87]
	v_mul_f32_e32 v24, v29, v29
	v_mul_f32_e32 v25, v31, v31
	v_fmac_f32_e32 v24, v28, v28
	v_fmac_f32_e32 v25, v30, v30
	v_add_f32_e32 v24, v24, v25
	v_mul_f32_e32 v25, v37, v37
	v_fmac_f32_e32 v25, v36, v36
	v_add_f32_e32 v24, v24, v25
	v_mul_f32_e32 v25, v35, v35
	v_fmac_f32_e32 v25, v34, v34
	v_add_f32_e32 v26, v25, v24
	v_pk_add_f32 v[24:25], v[18:19], v[82:83]
	v_pk_add_f32 v[18:19], v[16:17], v[80:81]
	v_mul_f32_e32 v17, v21, v21
	v_cvt_pk_bf16_f32 v16, v20, v21
	v_fmac_f32_e32 v17, v20, v20
	v_mul_f32_e32 v20, v23, v23
	v_fmac_f32_e32 v20, v22, v22
	v_add_f32_e32 v17, v17, v20
	v_mul_f32_e32 v20, v19, v19
	v_fmac_f32_e32 v20, v18, v18
	v_add_f32_e32 v17, v17, v20
	v_mul_f32_e32 v20, v25, v25
	v_fmac_f32_e32 v20, v24, v24
	v_add_f32_e32 v17, v20, v17
	v_add_f32_e32 v20, v26, v17
	ds_swizzle_b32 v21, v20 offset:swizzle(SWAP,16)
	v_cvt_pk_bf16_f32 v17, v22, v23
	v_cvt_pk_bf16_f32 v18, v18, v19
	v_cvt_pk_bf16_f32 v19, v24, v25
	flat_store_dwordx4 v[32:33], v[16:19] offset:64
	s_waitcnt lgkmcnt(0)
	s_nop 0
	v_add_f32_e32 v16, v20, v21
	v_mov_b32_e32 v17, v16
	s_nop 1
	v_permlane32_swap_b32_e32 v16, v17
	s_and_saveexec_b64 s[20:21], vcc
	s_cbranch_execz .LBB0_739
	v_add_f32_e32 v16, v16, v17
	global_atomic_add_f32 v[112:113], v16, off offset:640
.LBB0_739:
	s_or_b64 exec, exec, s[20:21]
	v_lshlrev_b64 v[16:17], 12, v[114:115]
	v_pk_add_f32 v[14:15], v[14:15], v[78:79]
	v_pk_add_f32 v[12:13], v[12:13], v[76:77]
	v_pk_add_f32 v[18:19], v[10:11], v[74:75]
	v_pk_add_f32 v[20:21], v[8:9], v[72:73]
	v_lshl_add_u64 v[16:17], s[10:11], 0, v[16:17]
	v_cvt_pk_bf16_f32 v8, v12, v13
	v_cvt_pk_bf16_f32 v9, v14, v15
	v_cvt_pk_bf16_f32 v10, v20, v21
	v_cvt_pk_bf16_f32 v11, v18, v19
	v_lshl_add_u64 v[16:17], v[188:189], 1, v[16:17]
	flat_store_dwordx4 v[16:17], v[8:11]
	v_pk_add_f32 v[4:5], v[4:5], v[68:69]
	v_pk_add_f32 v[6:7], v[6:7], v[70:71]
	v_mul_f32_e32 v8, v13, v13
	v_mul_f32_e32 v9, v15, v15
	v_fmac_f32_e32 v8, v12, v12
	v_fmac_f32_e32 v9, v14, v14
	v_add_f32_e32 v8, v8, v9
	v_mul_f32_e32 v9, v21, v21
	v_fmac_f32_e32 v9, v20, v20
	v_add_f32_e32 v8, v8, v9
	v_mul_f32_e32 v9, v19, v19
	v_fmac_f32_e32 v9, v18, v18
	v_add_f32_e32 v10, v9, v8
	v_pk_add_f32 v[8:9], v[2:3], v[66:67]
	v_pk_add_f32 v[2:3], v[0:1], v[64:65]
	v_mul_f32_e32 v1, v5, v5
	v_cvt_pk_bf16_f32 v0, v4, v5
	v_fmac_f32_e32 v1, v4, v4
	v_mul_f32_e32 v4, v7, v7
	v_fmac_f32_e32 v4, v6, v6
	v_add_f32_e32 v1, v1, v4
	v_mul_f32_e32 v4, v3, v3
	v_fmac_f32_e32 v4, v2, v2
	v_add_f32_e32 v1, v1, v4
	v_mul_f32_e32 v4, v9, v9
	v_fmac_f32_e32 v4, v8, v8
	v_add_f32_e32 v1, v4, v1
	v_add_f32_e32 v4, v10, v1
	ds_swizzle_b32 v5, v4 offset:swizzle(SWAP,16)
	v_cvt_pk_bf16_f32 v1, v6, v7
	v_cvt_pk_bf16_f32 v2, v2, v3
	v_cvt_pk_bf16_f32 v3, v8, v9
	flat_store_dwordx4 v[16:17], v[0:3] offset:64
	s_waitcnt lgkmcnt(0)
	s_nop 0
	v_add_f32_e32 v0, v4, v5
	v_mov_b32_e32 v1, v0
	s_nop 1
	v_permlane32_swap_b32_e32 v0, v1
	s_and_saveexec_b64 s[20:21], vcc
	s_cbranch_execz .LBB0_741
	v_add_f32_e32 v0, v0, v1
	global_atomic_add_f32 v[112:113], v0, off offset:704
